# scan recurrence as 4 fma per token (state ping-pongs between two register pairs) + BU tile to LDS with ds_write2_b32
# speedup vs baseline: 1.0267x; 1.0001x over previous
; #define LAS __attribute__((address_space(3)))
; template <bool PROJECT> ...
;     ...
;             const f32x4 a0 = *(const LAS f32x4*)(Ul + c * 16 + c0), a1 = *(const LAS f32x4*)(Ul + c * 16 + c0 + 4);
;             u32x4 wh; wh.x = cvt_pk_bf16(a0[0], a0[1]); wh.y = cvt_pk_bf16(a0[2], a0[3]); wh.z = cvt_pk_bf16(a1[0], a1[1]); wh.w = cvt_pk_bf16(a1[2], a1[3]);
;             u32x4 wl;
;             wl.x = cvt_pk_bf16(a0[0] - __uint_as_float(wh.x << 16), a0[1] - __uint_as_float(wh.x & 0xffff0000u)); wl.y = cvt_pk_bf16(a0[2] - __uint_as_float(wh.y << 16), a0[3] - __uint_as_float(wh.y & 0xffff0000u));
;             wl.z = cvt_pk_bf16(a1[0] - __uint_as_float(wh.z << 16), a1[1] - __uint_as_float(wh.z & 0xffff0000u)); wl.w = cvt_pk_bf16(a1[2] - __uint_as_float(wh.w << 16), a1[3] - __uint_as_float(wh.w & 0xffff0000u));
;             u32x4 wsel; wsel.x = part ? wl.x : wh.x; wsel.y = part ? wl.y : wh.y; wsel.z = part ? wl.z : wh.z; wsel.w = part ? wl.w : wh.w;
;             const bf16x8 aop = __builtin_bit_cast(bf16x8, wsel);
;             f32x4 br[4], bi[4];
; #pragma unroll
;             for (int i = 0; i < 4; ++i) {
;                 f32x4 zr = (f32x4){0.f, 0.f, 0.f, 0.f}, zi = zr;
;                 br[i] = __builtin_amdgcn_mfma_f32_16x16x32_bf16(aop, bop[0][i], zr, 0, 0, 0); bi[i] = __builtin_amdgcn_mfma_f32_16x16x32_bf16(aop, bop[1][i], zi, 0, 0, 0);
;             }
;             asm volatile("s_nop 15\n\ts_nop 15\n\ts_nop 15\n\ts_nop 15" : "+v"(br[0]), "+v"(br[1]), "+v"(br[2]), "+v"(br[3]), "+v"(bi[0]), "+v"(bi[1]), "+v"(bi[2]), "+v"(bi[3]), "+v"(wsel));
; #pragma unroll
;             for (int i = 0; i < 4; ++i)
; #pragma unroll
;                 for (int j = 0; j < 4; ++j) *(LAS f32x2v*)(BUl + (4 * tq + j) * BU_PITCH + 2 * (16 * i + c)) = (f32x2v){br[i][j], bi[i][j]};
;             asm volatile("s_waitcnt lgkmcnt(0)" ::: "memory"); __builtin_amdgcn_wave_barrier();
;         }
;         {
;             float bur[16], bui[16];
; #pragma unroll
;             for (int t = 0; t < 16; ++t) { const f32x2v bu = *(const LAS f32x2v*)(BUl + t * BU_PITCH + 2 * lane); bur[t] = bu.x; bui[t] = bu.y; }
; #pragma unroll
;             for (int t = 0; t < 16; ++t) {
;                 const float nre = lre * hre - lim * him + bur[t], nim = lre * him + lim * hre + bui[t];
;                 if (t < nsub) { hre = nre; him = nim; }
.LBB0_1464:
	v_add_u32_e32 v49, s28, v74
	ds_read_b128 v[76:79], v49
	ds_read_b128 v[80:83], v49 offset:16
	s_addk_i32 s28, 0x400
	s_cmpk_eq_i32 s28, 0x1000
	s_waitcnt lgkmcnt(0)
	v_cvt_pk_bf16_f32 v49, v76, v77
	s_nop 0
	v_lshlrev_b32_e32 v86, 16, v49
	v_sub_f32_e32 v76, v76, v86
	v_and_b32_e32 v86, 0xffff0000, v49
	v_sub_f32_e32 v77, v77, v86
	v_cvt_pk_bf16_f32 v75, v78, v79
	v_cvt_pk_bf16_f32 v84, v80, v81
	v_cvt_pk_bf16_f32 v85, v82, v83
	v_cvt_pk_bf16_f32 v76, v76, v77
	s_nop 0
	v_lshlrev_b32_e32 v77, 16, v75
	v_sub_f32_e32 v77, v78, v77
	v_and_b32_e32 v78, 0xffff0000, v75
	v_sub_f32_e32 v78, v79, v78
	v_cvt_pk_bf16_f32 v77, v77, v78
	v_lshlrev_b32_e32 v78, 16, v84
	v_and_b32_e32 v79, 0xffff0000, v84
	v_sub_f32_e32 v78, v80, v78
	v_sub_f32_e32 v79, v81, v79
	v_cvt_pk_bf16_f32 v78, v78, v79
	v_lshlrev_b32_e32 v79, 16, v85
	v_sub_f32_e32 v79, v82, v79
	v_and_b32_e32 v80, 0xffff0000, v85
	v_sub_f32_e32 v80, v83, v80
	v_cvt_pk_bf16_f32 v79, v79, v80
	v_cndmask_b32_e64 v76, v76, v49, s[46:47]
	v_cndmask_b32_e64 v77, v77, v75, s[46:47]
	v_cndmask_b32_e64 v78, v78, v84, s[46:47]
	v_cndmask_b32_e64 v79, v79, v85, s[46:47]
	v_add_u32_e32 v49, v169, v171
	v_add_u32_e32 v75, 0x2000, v49
	v_mfma_f32_16x16x32_bf16 v[80:83], v[76:79], v[0:3], 0
	v_add_u32_e32 v49, 0x2800, v49
	v_mfma_f32_16x16x32_bf16 v[84:87], v[76:79], v[4:7], 0
	v_mfma_f32_16x16x32_bf16 v[88:91], v[76:79], v[8:11], 0
	v_mfma_f32_16x16x32_bf16 v[92:95], v[76:79], v[12:15], 0
	v_mfma_f32_16x16x32_bf16 v[96:99], v[76:79], v[16:19], 0
	v_mfma_f32_16x16x32_bf16 v[100:103], v[76:79], v[20:23], 0
	v_mfma_f32_16x16x32_bf16 v[104:107], v[76:79], v[24:27], 0
	v_mfma_f32_16x16x32_bf16 v[108:111], v[76:79], v[28:31], 0
	s_nop 7
	s_nop 0
	v_add_u32_e32 v76, v169, v171
	v_add_u32_e32 v76, 0x2100, v76
	v_add_u32_e32 v77, 0x410, v76
	ds_write2_b32 v76, v80, v84 offset0:0 offset1:1
	ds_write2_b32 v76, v81, v85 offset0:130 offset1:131
	ds_write2_b32 v77, v82, v86 offset0:0 offset1:1
	ds_write2_b32 v77, v83, v87 offset0:130 offset1:131
	ds_write2_b32 v76, v88, v92 offset0:32 offset1:33
	ds_write2_b32 v76, v89, v93 offset0:162 offset1:163
	ds_write2_b32 v77, v90, v94 offset0:32 offset1:33
	ds_write2_b32 v77, v91, v95 offset0:162 offset1:163
	ds_write2_b32 v76, v96, v100 offset0:64 offset1:65
	ds_write2_b32 v76, v97, v101 offset0:194 offset1:195
	ds_write2_b32 v77, v98, v102 offset0:64 offset1:65
	ds_write2_b32 v77, v99, v103 offset0:194 offset1:195
	ds_write2_b32 v76, v104, v108 offset0:96 offset1:97
	ds_write2_b32 v76, v105, v109 offset0:226 offset1:227
	ds_write2_b32 v77, v106, v110 offset0:96 offset1:97
	ds_write2_b32 v77, v107, v111 offset0:226 offset1:227
	v_add_u32_e32 v49, s27, v166
	v_add_u32_e32 v75, 0x2000, v49
	s_waitcnt lgkmcnt(0)
	ds_read2_b64 v[76:79], v75 offset0:32 offset1:97
	ds_read2_b64 v[80:83], v75 offset0:162 offset1:227
	v_add_u32_e32 v75, 0x2800, v49
	ds_read2_b64 v[84:87], v75 offset0:36 offset1:101
	ds_read2_b64 v[88:91], v75 offset0:166 offset1:231
	v_add_u32_e32 v75, 0x3000, v49
	ds_read2_b64 v[92:95], v75 offset0:40 offset1:105
	ds_read2_b64 v[96:99], v75 offset0:170 offset1:235
	v_add_u32_e32 v49, 0x3800, v49
	ds_read2_b64 v[100:103], v49 offset0:44 offset1:109
	ds_read2_b64 v[104:107], v49 offset0:174 offset1:239
	s_waitcnt lgkmcnt(7)
	v_fma_f32 v108, -v53, v69, v76
	v_fma_f32 v109, v53, v68, v77
	v_fmac_f32_e32 v108, v52, v68
	v_fmac_f32_e32 v109, v52, v69
	v_fma_f32 v68, -v53, v109, v78
	v_fma_f32 v69, v53, v108, v79
	v_fmac_f32_e32 v68, v52, v108
	v_fmac_f32_e32 v69, v52, v109
	s_waitcnt lgkmcnt(6)
	v_fma_f32 v108, -v53, v69, v80
	v_fma_f32 v109, v53, v68, v81
	v_fmac_f32_e32 v108, v52, v68
	v_fmac_f32_e32 v109, v52, v69
	v_fma_f32 v68, -v53, v109, v82
	v_fma_f32 v69, v53, v108, v83
	v_fmac_f32_e32 v68, v52, v108
	v_fmac_f32_e32 v69, v52, v109
	s_waitcnt lgkmcnt(5)
	v_fma_f32 v108, -v53, v69, v84
	v_fma_f32 v109, v53, v68, v85
	v_fmac_f32_e32 v108, v52, v68
	v_fmac_f32_e32 v109, v52, v69
	v_fma_f32 v68, -v53, v109, v86
	v_fma_f32 v69, v53, v108, v87
	v_fmac_f32_e32 v68, v52, v108
	v_fmac_f32_e32 v69, v52, v109
	s_waitcnt lgkmcnt(4)
	v_fma_f32 v108, -v53, v69, v88
	v_fma_f32 v109, v53, v68, v89
	v_fmac_f32_e32 v108, v52, v68
	v_fmac_f32_e32 v109, v52, v69
	v_fma_f32 v68, -v53, v109, v90
	v_fma_f32 v69, v53, v108, v91
	v_fmac_f32_e32 v68, v52, v108
	v_fmac_f32_e32 v69, v52, v109
	s_waitcnt lgkmcnt(3)
	v_fma_f32 v108, -v53, v69, v92
	v_fma_f32 v109, v53, v68, v93
	v_fmac_f32_e32 v108, v52, v68
	v_fmac_f32_e32 v109, v52, v69
	v_fma_f32 v68, -v53, v109, v94
	v_fma_f32 v69, v53, v108, v95
	v_fmac_f32_e32 v68, v52, v108
	v_fmac_f32_e32 v69, v52, v109
	s_waitcnt lgkmcnt(2)
	v_fma_f32 v108, -v53, v69, v96
	v_fma_f32 v109, v53, v68, v97
	v_fmac_f32_e32 v108, v52, v68
	v_fmac_f32_e32 v109, v52, v69
	v_fma_f32 v68, -v53, v109, v98
	v_fma_f32 v69, v53, v108, v99
	v_fmac_f32_e32 v68, v52, v108
	v_fmac_f32_e32 v69, v52, v109
	s_waitcnt lgkmcnt(1)
	v_fma_f32 v108, -v53, v69, v100
	v_fma_f32 v109, v53, v68, v101
	v_fmac_f32_e32 v108, v52, v68
	v_fmac_f32_e32 v109, v52, v69
	v_fma_f32 v68, -v53, v109, v102
	v_fma_f32 v69, v53, v108, v103
	v_fmac_f32_e32 v68, v52, v108
	v_fmac_f32_e32 v69, v52, v109
	s_waitcnt lgkmcnt(0)
	v_fma_f32 v108, -v53, v69, v104
	v_fma_f32 v109, v53, v68, v105
	v_fmac_f32_e32 v108, v52, v68
	v_fmac_f32_e32 v109, v52, v69
	v_fma_f32 v68, -v53, v109, v106
	v_fma_f32 v69, v53, v108, v107
	v_fmac_f32_e32 v68, v52, v108
	v_fmac_f32_e32 v69, v52, v109
	s_cbranch_scc0 .LBB0_1464
	s_mov_b64 s[58:59], 0
	s_and_b64 vcc, exec, s[56:57]
	s_cbranch_vccz .LBB0_1461
	s_ashr_i32 s53, s52, 31
	s_mov_b32 s55, s29
	s_lshl_b64 s[6:7], s[52:53], 12
	s_lshl_b64 s[30:31], s[54:55], 6
	s_add_u32 s6, s30, s6
	s_addc_u32 s7, s31, s7
	s_or_b32 s6, s6, s4
	s_lshl_b64 s[6:7], s[6:7], 9
	s_add_i32 s26, s26, s66
	s_waitcnt vmcnt(3)
	v_lshl_add_u64 v[32:33], v[174:175], 0, s[6:7]
	s_cmpk_gt_i32 s26, 0x3ff
	global_store_dwordx2 v[32:33], v[68:69], off
	s_cbranch_scc0 .LBB0_1458

; template <bool PROJECT> ...
;     ...
;             const f32x4 a0 = *(const LAS f32x4*)(Ul + c * 16 + c0), a1 = *(const LAS f32x4*)(Ul + c * 16 + c0 + 4);
;             u32x4 wh; wh.x = cvt_pk_bf16(a0[0], a0[1]); wh.y = cvt_pk_bf16(a0[2], a0[3]); wh.z = cvt_pk_bf16(a1[0], a1[1]); wh.w = cvt_pk_bf16(a1[2], a1[3]);
;             u32x4 wl;
;             wl.x = cvt_pk_bf16(a0[0] - __uint_as_float(wh.x << 16), a0[1] - __uint_as_float(wh.x & 0xffff0000u)); wl.y = cvt_pk_bf16(a0[2] - __uint_as_float(wh.y << 16), a0[3] - __uint_as_float(wh.y & 0xffff0000u));
;             wl.z = cvt_pk_bf16(a1[0] - __uint_as_float(wh.z << 16), a1[1] - __uint_as_float(wh.z & 0xffff0000u)); wl.w = cvt_pk_bf16(a1[2] - __uint_as_float(wh.w << 16), a1[3] - __uint_as_float(wh.w & 0xffff0000u));
;             u32x4 wsel; wsel.x = part ? wl.x : wh.x; wsel.y = part ? wl.y : wh.y; wsel.z = part ? wl.z : wh.z; wsel.w = part ? wl.w : wh.w;
;             const bf16x8 aop = __builtin_bit_cast(bf16x8, wsel);
;             f32x4 br[4], bi[4];
; #pragma unroll
;             for (int i = 0; i < 4; ++i) {
;                 f32x4 zr = (f32x4){0.f, 0.f, 0.f, 0.f}, zi = zr;
;                 br[i] = __builtin_amdgcn_mfma_f32_16x16x32_bf16(aop, bop[0][i], zr, 0, 0, 0); bi[i] = __builtin_amdgcn_mfma_f32_16x16x32_bf16(aop, bop[1][i], zi, 0, 0, 0);
;             }
;             asm volatile("s_nop 15\n\ts_nop 15\n\ts_nop 15\n\ts_nop 15" : "+v"(br[0]), "+v"(br[1]), "+v"(br[2]), "+v"(br[3]), "+v"(bi[0]), "+v"(bi[1]), "+v"(bi[2]), "+v"(bi[3]), "+v"(wsel));
; #pragma unroll
;             for (int i = 0; i < 4; ++i)
; #pragma unroll
;                 for (int j = 0; j < 4; ++j) *(LAS f32x2v*)(BUl + (4 * tq + j) * BU_PITCH + 2 * (16 * i + c)) = (f32x2v){br[i][j], bi[i][j]};
;             asm volatile("s_waitcnt lgkmcnt(0)" ::: "memory"); __builtin_amdgcn_wave_barrier();
;         }
;         {
;             float bur[16], bui[16];
; #pragma unroll
;             for (int t = 0; t < 16; ++t) { const f32x2v bu = *(const LAS f32x2v*)(BUl + t * BU_PITCH + 2 * lane); bur[t] = bu.x; bui[t] = bu.y; }
; #pragma unroll
;             for (int t = 0; t < 16; ++t) {
;                 const float nre = lre * hre - lim * him + bur[t], nim = lre * him + lim * hre + bui[t];
;                 if (t < nsub) { hre = nre; him = nim; }
;                 if (PROJECT) *(LAS unsigned*)(Xb + t * XB_PITCH + 2 * lane) = cvt_pk_bf16(hre, him);
.LBB0_1543:
	ds_read_b128 v[112:115], v135
	ds_read_b128 v[136:139], v135 offset:16
	v_add_u32_e32 v135, 0x400, v135
	s_waitcnt lgkmcnt(1)
	v_cvt_pk_bf16_f32 v140, v112, v113
	s_nop 0
	v_lshlrev_b32_e32 v144, 16, v140
	v_sub_f32_e32 v112, v112, v144
	v_and_b32_e32 v144, 0xffff0000, v140
	v_sub_f32_e32 v113, v113, v144
	v_cvt_pk_bf16_f32 v141, v114, v115
	s_waitcnt lgkmcnt(0)
	v_cvt_pk_bf16_f32 v142, v136, v137
	v_cvt_pk_bf16_f32 v143, v138, v139
	v_cvt_pk_bf16_f32 v112, v112, v113
	v_lshlrev_b32_e32 v113, 16, v141
	v_sub_f32_e32 v113, v114, v113
	v_and_b32_e32 v114, 0xffff0000, v141
	v_sub_f32_e32 v114, v115, v114
	v_cvt_pk_bf16_f32 v113, v113, v114
	v_lshlrev_b32_e32 v114, 16, v142
	v_and_b32_e32 v115, 0xffff0000, v142
	v_sub_f32_e32 v114, v136, v114
	v_sub_f32_e32 v115, v137, v115
	v_cvt_pk_bf16_f32 v114, v114, v115
	v_lshlrev_b32_e32 v115, 16, v143
	v_sub_f32_e32 v115, v138, v115
	v_and_b32_e32 v136, 0xffff0000, v143
	v_sub_f32_e32 v136, v139, v136
	v_cvt_pk_bf16_f32 v115, v115, v136
	v_cndmask_b32_e64 v112, v112, v140, s[46:47]
	v_cndmask_b32_e64 v113, v113, v141, s[46:47]
	v_cndmask_b32_e64 v114, v114, v142, s[46:47]
	v_cndmask_b32_e64 v115, v115, v143, s[46:47]
	s_nop 1
	v_mfma_f32_16x16x32_bf16 v[136:139], v[112:115], v[48:51], 0
	v_mfma_f32_16x16x32_bf16 v[140:143], v[112:115], v[52:55], 0
	v_mfma_f32_16x16x32_bf16 v[144:147], v[112:115], v[56:59], 0
	v_mfma_f32_16x16x32_bf16 v[148:151], v[112:115], v[60:63], 0
	v_mfma_f32_16x16x32_bf16 v[152:155], v[112:115], v[64:67], 0
	v_mfma_f32_16x16x32_bf16 v[156:159], v[112:115], v[68:71], 0
	v_mfma_f32_16x16x32_bf16 v[204:207], v[112:115], v[72:75], 0
	v_mfma_f32_16x16x32_bf16 v[208:211], v[112:115], v[76:79], 0
	s_nop 7
	s_nop 0
	v_add_u32_e32 v114, v169, v171
	v_add_u32_e32 v114, 0x2100, v114
	v_add_u32_e32 v115, 0x410, v114
	ds_write2_b32 v114, v136, v140 offset0:0 offset1:1
	ds_write2_b32 v114, v137, v141 offset0:130 offset1:131
	ds_write2_b32 v115, v138, v142 offset0:0 offset1:1
	ds_write2_b32 v115, v139, v143 offset0:130 offset1:131
	ds_write2_b32 v114, v144, v148 offset0:32 offset1:33
	ds_write2_b32 v114, v145, v149 offset0:162 offset1:163
	ds_write2_b32 v115, v146, v150 offset0:32 offset1:33
	ds_write2_b32 v115, v147, v151 offset0:162 offset1:163
	ds_write2_b32 v114, v152, v156 offset0:64 offset1:65
	ds_write2_b32 v114, v153, v157 offset0:194 offset1:195
	ds_write2_b32 v115, v154, v158 offset0:64 offset1:65
	ds_write2_b32 v115, v155, v159 offset0:194 offset1:195
	ds_write2_b32 v114, v204, v208 offset0:96 offset1:97
	ds_write2_b32 v114, v205, v209 offset0:226 offset1:227
	ds_write2_b32 v115, v206, v210 offset0:96 offset1:97
	ds_write2_b32 v115, v207, v211 offset0:226 offset1:227
	v_add_u32_e32 v156, s27, v166
	v_add_u32_e32 v136, 0x2000, v156
	s_waitcnt lgkmcnt(0)
	ds_read2_b64 v[112:115], v136 offset0:32 offset1:97
	ds_read2_b64 v[136:139], v136 offset0:162 offset1:227
	v_add_u32_e32 v144, 0x2800, v156
	v_add_u32_e32 v152, 0x3000, v156
	v_add_u32_e32 v180, 0x3800, v156
	ds_read2_b64 v[140:143], v144 offset0:36 offset1:101
	ds_read2_b64 v[144:147], v144 offset0:166 offset1:231
	ds_read2_b64 v[148:151], v152 offset0:40 offset1:105
	ds_read2_b64 v[152:155], v152 offset0:170 offset1:235
	ds_read2_b64 v[156:159], v180 offset0:44 offset1:109
	ds_read2_b64 v[204:207], v180 offset0:174 offset1:239
	v_add_u32_e32 v208, s27, v164
	s_waitcnt lgkmcnt(7)
	v_fma_f32 v190, -v187, v189, v112
	v_fma_f32 v191, v187, v188, v113
	v_fmac_f32_e32 v190, v186, v188
	v_fmac_f32_e32 v191, v186, v189
	v_cvt_pk_bf16_f32 v180, v190, v191
	ds_write_b32 v208, v180 offset:4096
	v_fma_f32 v188, -v187, v191, v114
	v_fma_f32 v189, v187, v190, v115
	v_fmac_f32_e32 v188, v186, v190
	v_fmac_f32_e32 v189, v186, v191
	v_cvt_pk_bf16_f32 v180, v188, v189
	ds_write_b32 v208, v180 offset:4368
	s_waitcnt lgkmcnt(8)
	v_fma_f32 v190, -v187, v189, v136
	v_fma_f32 v191, v187, v188, v137
	v_fmac_f32_e32 v190, v186, v188
	v_fmac_f32_e32 v191, v186, v189
	v_cvt_pk_bf16_f32 v180, v190, v191
	ds_write_b32 v208, v180 offset:4640
	v_fma_f32 v188, -v187, v191, v138
	v_fma_f32 v189, v187, v190, v139
	v_fmac_f32_e32 v188, v186, v190
	v_fmac_f32_e32 v189, v186, v191
	v_cvt_pk_bf16_f32 v180, v188, v189
	ds_write_b32 v208, v180 offset:4912
	s_waitcnt lgkmcnt(9)
	v_fma_f32 v190, -v187, v189, v140
	v_fma_f32 v191, v187, v188, v141
	v_fmac_f32_e32 v190, v186, v188
	v_fmac_f32_e32 v191, v186, v189
	v_cvt_pk_bf16_f32 v180, v190, v191
	ds_write_b32 v208, v180 offset:5184
	v_fma_f32 v188, -v187, v191, v142
	v_fma_f32 v189, v187, v190, v143
	v_fmac_f32_e32 v188, v186, v190
	v_fmac_f32_e32 v189, v186, v191
	v_cvt_pk_bf16_f32 v180, v188, v189
	ds_write_b32 v208, v180 offset:5456
	s_waitcnt lgkmcnt(10)
	v_fma_f32 v190, -v187, v189, v144
	v_fma_f32 v191, v187, v188, v145
	v_fmac_f32_e32 v190, v186, v188
	v_fmac_f32_e32 v191, v186, v189
	v_cvt_pk_bf16_f32 v180, v190, v191
	ds_write_b32 v208, v180 offset:5728
	v_fma_f32 v188, -v187, v191, v146
	v_fma_f32 v189, v187, v190, v147
	v_fmac_f32_e32 v188, v186, v190
	v_fmac_f32_e32 v189, v186, v191
	v_cvt_pk_bf16_f32 v180, v188, v189
	ds_write_b32 v208, v180 offset:6000
	s_waitcnt lgkmcnt(11)
	v_fma_f32 v190, -v187, v189, v148
	v_fma_f32 v191, v187, v188, v149
	v_fmac_f32_e32 v190, v186, v188
	v_fmac_f32_e32 v191, v186, v189
	v_cvt_pk_bf16_f32 v180, v190, v191
	ds_write_b32 v208, v180 offset:6272
	v_fma_f32 v188, -v187, v191, v150
	v_fma_f32 v189, v187, v190, v151
	v_fmac_f32_e32 v188, v186, v190
	v_fmac_f32_e32 v189, v186, v191
	v_cvt_pk_bf16_f32 v180, v188, v189
	ds_write_b32 v208, v180 offset:6544
	s_waitcnt lgkmcnt(12)
; __device__ __forceinline__ unsigned cvt_pk_bf16(float lo, float hi) { unsigned r; asm volatile("v_cvt_pk_bf16_f32 %0, %1, %2" : "=v"(r) : "v"(lo), "v"(hi)); return r; }
; #define LAS __attribute__((address_space(3)))
; template <bool PROJECT> ...
;     ...
; #pragma unroll
;             for (int t = 0; t < 16; ++t) {
;                 const float nre = lre * hre - lim * him + bur[t], nim = lre * him + lim * hre + bui[t];
;                 if (t < nsub) { hre = nre; him = nim; }
;                 if (PROJECT) *(LAS unsigned*)(Xb + t * XB_PITCH + 2 * lane) = cvt_pk_bf16(hre, him);
;             }
;         }
;         if (PROJECT) {
;             asm volatile("s_waitcnt lgkmcnt(0)" ::: "memory"); __builtin_amdgcn_wave_barrier();
;             f32x4 y = (f32x4){0.f, 0.f, 0.f, 0.f};
; #pragma unroll
;             for (int ks = 0; ks < 4; ++ks) { const bf16x8 ax = *(const LAS bf16x8*)(Xb + c * XB_PITCH + 32 * ks + 8 * tq); y = __builtin_amdgcn_mfma_f32_16x16x32_bf16(ax, cop[ks], y, 0, 0, 0); }
; #pragma unroll
;             for (int i = 0; i < 4; ++i) { const int t = 4 * tq + i;
;                 if (t < nsub) { const float v = y[i] + dv * Ul[t * 16 + c];
;                     gbuf[(size_t)(row0 + t0 + t) * D + g * 16 + c] = (bf16_t)(cvt_pk_bf16(gelu_tanh(v), 0.f) & 0xffffu); } }
;             asm volatile("s_waitcnt lgkmcnt(0)" ::: "memory"); __builtin_amdgcn_wave_barrier();
	v_fma_f32 v190, -v187, v189, v152
	v_fma_f32 v191, v187, v188, v153
	v_fmac_f32_e32 v190, v186, v188
	v_fmac_f32_e32 v191, v186, v189
	v_cvt_pk_bf16_f32 v180, v190, v191
	ds_write_b32 v208, v180 offset:6816
	v_fma_f32 v188, -v187, v191, v154
	v_fma_f32 v189, v187, v190, v155
	v_fmac_f32_e32 v188, v186, v190
	v_fmac_f32_e32 v189, v186, v191
	v_cvt_pk_bf16_f32 v180, v188, v189
	ds_write_b32 v208, v180 offset:7088
	s_waitcnt lgkmcnt(13)
	v_fma_f32 v190, -v187, v189, v156
	v_fma_f32 v191, v187, v188, v157
	v_fmac_f32_e32 v190, v186, v188
	v_fmac_f32_e32 v191, v186, v189
	v_cvt_pk_bf16_f32 v180, v190, v191
	ds_write_b32 v208, v180 offset:7360
	v_fma_f32 v188, -v187, v191, v158
	v_fma_f32 v189, v187, v190, v159
	v_fmac_f32_e32 v188, v186, v190
	v_fmac_f32_e32 v189, v186, v191
	v_cvt_pk_bf16_f32 v180, v188, v189
	ds_write_b32 v208, v180 offset:7632
	s_waitcnt lgkmcnt(14)
	v_fma_f32 v190, -v187, v189, v204
	v_fma_f32 v191, v187, v188, v205
	v_fmac_f32_e32 v190, v186, v188
	v_fmac_f32_e32 v191, v186, v189
	v_cvt_pk_bf16_f32 v180, v190, v191
	ds_write_b32 v208, v180 offset:7904
	v_fma_f32 v188, -v187, v191, v206
	v_fma_f32 v189, v187, v190, v207
	v_fmac_f32_e32 v188, v186, v190
	v_fmac_f32_e32 v189, v186, v191
	v_cvt_pk_bf16_f32 v180, v188, v189
	ds_write_b32 v208, v180 offset:8176
	v_add_u32_e32 v112, v199, v162
	s_waitcnt lgkmcnt(0)
	ds_read_b128 v[136:139], v112 offset:4096
	ds_read_b128 v[140:143], v112 offset:4160
	s_waitcnt lgkmcnt(1)
	v_mfma_f32_16x16x32_bf16 v[136:139], v[136:139], v[92:95], 0
	s_waitcnt lgkmcnt(0)
	v_mfma_f32_16x16x32_bf16 v[136:139], v[140:143], v[80:83], v[136:139]
	ds_read_b128 v[140:143], v112 offset:4224
	ds_read_b128 v[112:115], v112 offset:4288
	s_waitcnt lgkmcnt(1)
	v_mfma_f32_16x16x32_bf16 v[136:139], v[140:143], v[84:87], v[136:139]
	s_waitcnt lgkmcnt(0)
	v_mfma_f32_16x16x32_bf16 v[112:115], v[112:115], v[88:91], v[136:139]
	s_nop 5
	ds_read_b32 v136, v134
	s_waitcnt lgkmcnt(0)
	v_fma_f32 v112, v203, v136, v112
	v_mul_f32_e32 v136, 0x3d372713, v112
	v_mul_f32_e32 v136, v112, v136
	v_fma_f32 v136, v112, v136, v112
	v_mul_f32_e32 v136, 0x3f4c422a, v136
	v_add_f32_e32 v136, v136, v136
	v_mul_f32_e32 v136, 0x3fb8aa3b, v136
	v_exp_f32_e32 v136, v136
	v_mul_f32_e32 v112, 0.5, v112
	v_add_f32_e32 v136, 1.0, v136
	v_rcp_f32_e32 v136, v136
	s_nop 0
	v_fma_f32 v136, v136, -2.0, 1.0
	v_add_f32_e32 v136, 1.0, v136
	v_mul_f32_e32 v112, v112, v136
	v_add_u32_e32 v136, s4, v133
	v_ashrrev_i32_e32 v137, 31, v136
	v_lshlrev_b64 v[138:139], 11, v[136:137]
	v_cvt_pk_bf16_f32 v112, v112, v181
	v_lshl_add_u64 v[138:139], v[116:117], 0, v[138:139]
	global_store_short v[138:139], v112, off
	ds_read_b32 v112, v134 offset:64
	s_add_i32 s4, s4, 16
	s_cmp_lg_u32 s4, 64
	s_waitcnt lgkmcnt(0)
	v_fma_f32 v112, v203, v112, v113
	v_mul_f32_e32 v113, 0x3d372713, v112
	v_mul_f32_e32 v113, v112, v113
	v_fma_f32 v113, v112, v113, v112
	v_mul_f32_e32 v113, 0x3f4c422a, v113
	v_add_f32_e32 v113, v113, v113
	v_mul_f32_e32 v113, 0x3fb8aa3b, v113
	v_exp_f32_e32 v113, v113
	v_mul_f32_e32 v112, 0.5, v112
	v_add_f32_e32 v113, 1.0, v113
	v_rcp_f32_e32 v113, v113
	s_nop 0
	v_fma_f32 v113, v113, -2.0, 1.0
	v_add_f32_e32 v113, 1.0, v113
	v_mul_f32_e32 v112, v112, v113
	v_cvt_pk_bf16_f32 v137, v112, v181
	v_add_u32_e32 v112, 1, v136
	v_ashrrev_i32_e32 v113, 31, v112
	v_lshlrev_b64 v[112:113], 11, v[112:113]
	v_lshl_add_u64 v[112:113], v[116:117], 0, v[112:113]
	global_store_short v[112:113], v137, off
	ds_read_b32 v112, v134 offset:128
	s_waitcnt lgkmcnt(0)
	v_fma_f32 v112, v203, v112, v114
	v_mul_f32_e32 v113, 0x3d372713, v112
	v_mul_f32_e32 v113, v112, v113
	v_fma_f32 v113, v112, v113, v112
	v_mul_f32_e32 v113, 0x3f4c422a, v113
	v_add_f32_e32 v113, v113, v113
	v_mul_f32_e32 v113, 0x3fb8aa3b, v113
	v_exp_f32_e32 v113, v113
	v_mul_f32_e32 v112, 0.5, v112
	v_add_f32_e32 v113, 1.0, v113
	v_rcp_f32_e32 v113, v113
	s_nop 0
	v_fma_f32 v113, v113, -2.0, 1.0
	v_add_f32_e32 v113, 1.0, v113
	v_mul_f32_e32 v112, v112, v113
	v_cvt_pk_bf16_f32 v114, v112, v181
	v_add_u32_e32 v112, 2, v136
	v_ashrrev_i32_e32 v113, 31, v112
	v_lshlrev_b64 v[112:113], 11, v[112:113]
	v_lshl_add_u64 v[112:113], v[116:117], 0, v[112:113]
	global_store_short v[112:113], v114, off
	ds_read_b32 v112, v134 offset:192
	v_add_u32_e32 v134, 0x400, v134
	s_waitcnt lgkmcnt(0)
	v_fmac_f32_e32 v115, v203, v112
	v_mul_f32_e32 v112, 0x3d372713, v115
	v_mul_f32_e32 v112, v115, v112
	v_fma_f32 v112, v115, v112, v115
	v_mul_f32_e32 v112, 0x3f4c422a, v112
	v_add_f32_e32 v112, v112, v112
	v_mul_f32_e32 v112, 0x3fb8aa3b, v112
	v_exp_f32_e32 v112, v112
	v_mul_f32_e32 v113, 0.5, v115
	v_add_f32_e32 v112, 1.0, v112
	v_rcp_f32_e32 v112, v112
	s_nop 0
	v_fma_f32 v112, v112, -2.0, 1.0
	v_add_f32_e32 v112, 1.0, v112
	v_mul_f32_e32 v112, v113, v112
	v_cvt_pk_bf16_f32 v114, v112, v181
	v_add_u32_e32 v112, 3, v136
	v_ashrrev_i32_e32 v113, 31, v112
	v_lshlrev_b64 v[112:113], 11, v[112:113]
	v_lshl_add_u64 v[112:113], v[116:117], 0, v[112:113]
	global_store_short v[112:113], v114, off
	s_waitcnt lgkmcnt(0)
	s_cbranch_scc1 .LBB0_1543
	s_mov_b32 s4, 64
	s_andn2_b64 vcc, exec, s[28:29]
	s_mov_b64 s[48:49], 0
	s_cbranch_vccz .LBB0_1546
	s_mov_b64 s[28:29], -1
	s_branch .LBB0_1540
